# attention: lazy-rescale softmax (thr 8, -m folded in MFMA C), row-sum via ones-MFMA, K/bias LDS prefetch before barrier, ring writes at step tail
# speedup vs baseline: 1.0285x; 1.0125x over previous
.LBB0_121:
	s_or_b64 exec, exec, s[0:1]
	s_lshl_b32 s0, s14, 11
	s_waitcnt vmcnt(0)
	v_add_u32_e32 v0, s0, v79
	v_ashrrev_i32_e32 v1, 31, v0
	v_readlane_b32 s4, v251, 6
	v_lshlrev_b64 v[0:1], 12, v[0:1]
	v_readlane_b32 s5, v251, 7
	s_lshl_b32 s26, s13, 1
	v_readlane_b32 s2, v251, 8
	v_lshl_add_u64 v[0:1], s[4:5], 0, v[0:1]
	v_lshl_add_u64 v[0:1], v[0:1], 0, s[26:27]
	v_readlane_b32 s3, v251, 9
	v_lshl_add_u64 v[70:71], v[0:1], 0, v[152:153]
	v_add_u32_e32 v2, s13, v79
	v_mov_b64_e32 v[0:1], s[2:3]
	v_mad_i64_i32 v[0:1], s[2:3], v2, s23, v[0:1]
	s_ashr_i32 s1, s0, 31
	v_lshl_add_u64 v[0:1], s[0:1], 1, v[0:1]
	v_lshl_add_u64 v[72:73], v[0:1], 0, v[152:153]
	global_load_dwordx4 v[0:3], v[70:71], off offset:2048
	global_load_dwordx4 v[4:7], v[72:73], off
	global_load_dwordx4 v[8:11], v[72:73], off offset:128
	s_mov_b32 s1, 0x40000
	v_add_co_u32_e32 v12, vcc, s1, v70
	s_add_i32 s2, s10, s0
	s_nop 0
	v_addc_co_u32_e32 v13, vcc, 0, v71, vcc
	global_load_dwordx4 v[12:15], v[12:13], off offset:2048
	v_or_b32_e32 v20, s2, v63
	v_ashrrev_i32_e32 v21, 31, v20
	v_add_co_u32_e32 v24, vcc, s25, v70
	v_lshlrev_b64 v[20:21], 12, v[20:21]
	s_nop 0
	v_addc_co_u32_e32 v25, vcc, 0, v71, vcc
	v_lshl_add_u64 v[20:21], s[4:5], 0, v[20:21]
	v_add_co_u32_e32 v26, vcc, s31, v70
	v_add_u32_e32 v96, 0x18c00, v92
	v_lshl_add_u64 v[20:21], v[20:21], 0, s[26:27]
	v_addc_co_u32_e32 v27, vcc, 0, v71, vcc
	v_add_u32_e32 v93, 0x12000, v92
	v_add_u32_e32 v94, 0x14400, v92
	v_add_u32_e32 v95, 0x16800, v92
	global_load_dwordx4 v[16:19], v[72:73], off offset:256
	v_lshl_add_u64 v[32:33], v[56:57], 1, v[20:21]
	global_load_dwordx4 v[20:23], v[72:73], off offset:384
	global_load_dwordx4 v[28:31], v[24:25], off offset:2048
	s_nop 0
	global_load_dwordx4 v[24:27], v[26:27], off offset:2048
	v_mov_b32_e32 v100, 0
	s_mov_b32 s1, 0
	s_or_b32 s0, s0, s8
	v_lshl_add_u64 v[74:75], v[58:59], 0, s[26:27]
	v_lshl_add_u64 v[76:77], v[60:61], 0, s[26:27]
	v_mov_b32_e32 v101, 0xf149f2ca
	s_mov_b32 s15, 4
	s_mov_b32 s5, 8
	s_mov_b32 s3, -3
	v_mov_b32_e32 v97, 0
	v_mov_b32_e32 v98, 8
	v_mov_b32_e32 v99, 0
	s_mov_b32 s14, 0
	s_mov_b32 s13, s9
	s_mov_b32 s4, 0
	s_mov_b32 s16, 4
	v_mov_b32_e32 v34, v100
	v_mov_b32_e32 v35, v100
	v_mov_b32_e32 v36, v100
	v_mov_b32_e32 v37, v100
	v_mov_b32_e32 v38, v100
	v_mov_b32_e32 v39, v100
	v_mov_b32_e32 v40, v100
	v_mov_b32_e32 v41, v100
	v_mov_b32_e32 v42, v100
	v_mov_b32_e32 v43, v100
	v_mov_b32_e32 v44, v100
	v_mov_b32_e32 v45, v100
	v_mov_b32_e32 v46, v100
	v_mov_b32_e32 v47, v100
	s_waitcnt vmcnt(0)
	ds_write_b128 v96, v[8:11]
	ds_write_b128 v94, v[4:7]
	ds_write_b128 v93, v[0:3]
	s_waitcnt vmcnt(4)
	ds_write_b128 v95, v[12:15]
	s_waitcnt lgkmcnt(0)
	s_barrier
	global_load_dwordx4 v[0:3], v[32:33], off
	global_load_dwordx4 v[4:7], v[32:33], off offset:64
	v_mov_b32_e32 v8, v153
	v_mov_b32_e32 v9, v153
	v_mov_b32_e32 v10, v153
	v_mov_b32_e32 v11, v153
	v_mov_b32_e32 v12, v153
	v_mov_b32_e32 v13, v153
	v_mov_b32_e32 v14, v153
	v_mov_b32_e32 v15, v153
	v_mov_b32_e32 v32, 0
	v_mov_b32_e32 v33, v100
	v_add_u32_e32 v210, v82, v81
	v_add_u32_e32 v211, v83, v80
	v_add_u32_e32 v226, 0x1b000, v92
	v_add_u32_e32 v227, 0x1d400, v92
	v_mov_b32_e32 v144, 0x3f803f80
	v_mov_b32_e32 v145, v144
	v_mov_b32_e32 v146, v144
	v_mov_b32_e32 v147, v144
	v_sub_u32_e32 v102, v97, v99
	v_add_u32_e32 v102, s14, v102
	v_cmp_gt_u32_e32 vcc, 8, v102
	s_cbranch_vccz .Lpf_skip_init
	v_mad_u32_u24 v103, v102, s34, v67
	v_subrev_u32_e32 v120, s13, v99
	ds_read_b128 v[166:169], v103 offset:3072
	ds_read_b128 v[174:177], v103 offset:5376
	ds_read_b128 v[170:173], v103 offset:3136
	ds_read_b128 v[178:181], v103 offset:5440
	v_add3_u32 v120, v120, v102, 7
	ds_read_b128 v[182:185], v210 offset:0
	ds_read_b128 v[190:193], v210 offset:576
	ds_read_b128 v[186:189], v210 offset:64
	ds_read_b128 v[194:197], v210 offset:640
	v_mul_u32_u24_e32 v120, 0xc0, v120
	v_lshl_add_u32 v121, v84, 2, v120
	v_lshl_add_u32 v122, v86, 2, v120
	v_lshl_add_u32 v123, v88, 2, v120
	v_lshl_add_u32 v124, v90, 2, v120
	v_lshl_add_u32 v125, v85, 2, v120
	v_lshl_add_u32 v126, v87, 2, v120
	v_lshl_add_u32 v127, v89, 2, v120
	v_lshl_add_u32 v120, v91, 2, v120
	ds_read_b32 v112, v121
	ds_read_b32 v113, v122
	ds_read_b32 v114, v123
	ds_read_b32 v115, v124
	ds_read_b32 v116, v125
	ds_read_b32 v117, v126
	ds_read_b32 v118, v127
	ds_read_b32 v119, v120
	s_waitcnt lgkmcnt(15)
	s_branch .Lpf_done_init
.Lpf_skip_init:
	s_waitcnt lgkmcnt(0)

.LBB0_122:
	s_waitcnt vmcnt(4)
	ds_write_b128 v95, v[48:51]
	ds_write_b128 v96, v[52:55]
	v_sub_u32_e32 v102, v97, v99
	v_add_u32_e32 v102, s14, v102
	v_cmp_gt_u32_e32 vcc, 8, v102
	s_cbranch_vccz .Lpf_skip_a
	v_mad_u32_u24 v103, v102, s34, v67
	v_subrev_u32_e32 v120, s13, v99
	ds_read_b128 v[166:169], v103 offset:3072
	ds_read_b128 v[174:177], v103 offset:5376
	ds_read_b128 v[170:173], v103 offset:3136
	ds_read_b128 v[178:181], v103 offset:5440
	v_add3_u32 v120, v120, v102, 7
	ds_read_b128 v[182:185], v210 offset:0
	ds_read_b128 v[190:193], v210 offset:576
	ds_read_b128 v[186:189], v210 offset:64
	ds_read_b128 v[194:197], v210 offset:640
	v_mul_u32_u24_e32 v120, 0xc0, v120
	v_lshl_add_u32 v121, v84, 2, v120
	v_lshl_add_u32 v122, v86, 2, v120
	v_lshl_add_u32 v123, v88, 2, v120
	v_lshl_add_u32 v124, v90, 2, v120
	v_lshl_add_u32 v125, v85, 2, v120
	v_lshl_add_u32 v126, v87, 2, v120
	v_lshl_add_u32 v127, v89, 2, v120
	v_lshl_add_u32 v120, v91, 2, v120
	ds_read_b32 v112, v121
	ds_read_b32 v113, v122
	ds_read_b32 v114, v123
	ds_read_b32 v115, v124
	ds_read_b32 v116, v125
	ds_read_b32 v117, v126
	ds_read_b32 v118, v127
	ds_read_b32 v119, v120
	s_waitcnt lgkmcnt(15)
	s_branch .Lpf_done_a

.Lpf_done_a:
	s_barrier
	s_add_i32 s3, s3, 3
	s_cmpk_gt_u32 s3, 0x89
	s_cbranch_scc1 .LBB0_110

.LBB0_133:
	s_cmp_lt_i32 s4, 16
	s_cselect_b32 s18, s15, 0
	s_ashr_i32 s19, s18, 31
	s_lshl_b64 s[20:21], s[18:19], 18
	s_lshl_b32 s18, s18, 6
	s_ashr_i32 s19, s18, 31
	s_waitcnt vmcnt(4)
	ds_write_b128 v226, v[28:31]
	ds_write_b128 v227, v[16:19]
	v_sub_u32_e32 v102, v97, v99
	v_add_u32_e32 v102, s14, v102
	v_cmp_gt_u32_e32 vcc, 8, v102
	s_cbranch_vccz .Lpf_skip_b
	v_mad_u32_u24 v103, v102, s34, v67
	v_subrev_u32_e32 v120, s13, v99
	ds_read_b128 v[166:169], v103 offset:3072
	ds_read_b128 v[174:177], v103 offset:5376
	ds_read_b128 v[170:173], v103 offset:3136
	ds_read_b128 v[178:181], v103 offset:5440
	v_add3_u32 v120, v120, v102, 7
	ds_read_b128 v[182:185], v210 offset:18432
	ds_read_b128 v[190:193], v210 offset:19008
	ds_read_b128 v[186:189], v210 offset:18496
	ds_read_b128 v[194:197], v210 offset:19072
	v_mul_u32_u24_e32 v120, 0xc0, v120
	v_lshl_add_u32 v121, v84, 2, v120
	v_lshl_add_u32 v122, v86, 2, v120
	v_lshl_add_u32 v123, v88, 2, v120
	v_lshl_add_u32 v124, v90, 2, v120
	v_lshl_add_u32 v125, v85, 2, v120
	v_lshl_add_u32 v126, v87, 2, v120
	v_lshl_add_u32 v127, v89, 2, v120
	v_lshl_add_u32 v120, v91, 2, v120
	ds_read_b32 v112, v121
	ds_read_b32 v113, v122
	ds_read_b32 v114, v123
	ds_read_b32 v115, v124
	ds_read_b32 v116, v125
	ds_read_b32 v117, v126
	ds_read_b32 v118, v127
	ds_read_b32 v119, v120
	s_waitcnt lgkmcnt(15)
	s_branch .Lpf_done_b

.Lpf_done_b:
	s_barrier
	v_lshl_add_u64 v[16:17], v[70:71], 0, s[20:21]
	v_lshl_add_u64 v[18:19], s[18:19], 1, v[72:73]
	global_load_dwordx4 v[28:31], v[16:17], off offset:2048
	s_nop 0
	global_load_dwordx4 v[16:19], v[18:19], off
	s_add_i32 s17, s17, 1
	v_cmp_lt_i32_e32 vcc, s17, v98
	s_cbranch_vccnz .LBB0_135
	s_add_i32 s4, s4, 1
	s_lshl_b32 s15, s4, 1
	v_med3_i32 v98, s15, 4, 28
	s_or_b32 s15, s15, 1
	v_med3_i32 v102, s15, 4, 28
	v_readfirstlane_b32 s16, v98
	v_sub_u32_e32 v98, v102, v98
	s_add_i32 s16, s16, -4
	v_add_u32_e32 v98, 8, v98
	s_mov_b32 s17, 0
	s_cmp_gt_i32 s1, 15
	s_cbranch_scc0 .LBB0_136
	s_branch .LBB0_143

.LBB0_143:
	s_cmp_lt_i32 s4, 16
	s_cselect_b32 s18, s16, 0
	s_ashr_i32 s19, s18, 31
	s_lshl_b64 s[20:21], s[18:19], 18
	s_lshl_b32 s18, s18, 6
	s_ashr_i32 s19, s18, 31
	s_waitcnt vmcnt(4)
	ds_write_b128 v93, v[24:27]
	ds_write_b128 v94, v[20:23]
	v_sub_u32_e32 v102, v97, v99
	v_add_u32_e32 v102, s14, v102
	v_cmp_gt_u32_e32 vcc, 8, v102
	s_cbranch_vccz .Lpf_skip_c
	v_mad_u32_u24 v103, v102, s34, v67
	v_subrev_u32_e32 v120, s13, v99
	ds_read_b128 v[166:169], v103 offset:3072
	ds_read_b128 v[174:177], v103 offset:5376
	ds_read_b128 v[170:173], v103 offset:3136
	ds_read_b128 v[178:181], v103 offset:5440
	v_add3_u32 v120, v120, v102, 7
	ds_read_b128 v[182:185], v210 offset:36864
	ds_read_b128 v[190:193], v210 offset:37440
	ds_read_b128 v[186:189], v210 offset:36928
	ds_read_b128 v[194:197], v210 offset:37504
	v_mul_u32_u24_e32 v120, 0xc0, v120
	v_lshl_add_u32 v121, v84, 2, v120
	v_lshl_add_u32 v122, v86, 2, v120
	v_lshl_add_u32 v123, v88, 2, v120
	v_lshl_add_u32 v124, v90, 2, v120
	v_lshl_add_u32 v125, v85, 2, v120
	v_lshl_add_u32 v126, v87, 2, v120
	v_lshl_add_u32 v127, v89, 2, v120
	v_lshl_add_u32 v120, v91, 2, v120
	ds_read_b32 v112, v121
	ds_read_b32 v113, v122
	ds_read_b32 v114, v123
	ds_read_b32 v115, v124
	ds_read_b32 v116, v125
	ds_read_b32 v117, v126
	ds_read_b32 v118, v127
	ds_read_b32 v119, v120
	s_waitcnt lgkmcnt(15)
	s_branch .Lpf_done_c

.Lpf_done_c:
	s_barrier
	v_lshl_add_u64 v[20:21], v[70:71], 0, s[20:21]
	v_lshl_add_u64 v[22:23], s[18:19], 1, v[72:73]
	global_load_dwordx4 v[24:27], v[20:21], off offset:2048
	s_nop 0
	global_load_dwordx4 v[20:23], v[22:23], off
	s_add_i32 s15, s17, 1
	v_cmp_lt_i32_e32 vcc, s15, v98
	s_cbranch_vccnz .LBB0_145
	s_add_i32 s4, s4, 1
	s_lshl_b32 s15, s4, 1
	v_med3_i32 v98, s15, 4, 28
	s_or_b32 s15, s15, 1
	v_med3_i32 v102, s15, 4, 28
	v_readfirstlane_b32 s16, v98
	v_sub_u32_e32 v98, v102, v98
	s_add_i32 s16, s16, -4
	v_add_u32_e32 v98, 8, v98
	s_mov_b32 s15, 0
	s_cmp_gt_i32 s1, 15
	s_cbranch_scc1 .LBB0_122
	s_branch .LBB0_146

.Lrare_a:
	v_mov_b32_e32 v122, v121
	s_nop 1
	v_permlane16_swap_b32_e32 v121, v122
	v_max_f32_e32 v121, v121, v122
	v_mov_b32_e32 v122, v121
	s_nop 1
	v_permlane32_swap_b32_e32 v121, v122
	v_max3_f32 v121, v121, v122, 0
	v_exp_f32_e64 v164, -v121
	v_sub_f32_e32 v104, v104, v121
	v_sub_f32_e32 v105, v105, v121
	v_sub_f32_e32 v106, v106, v121
	v_sub_f32_e32 v107, v107, v121
	v_sub_f32_e32 v108, v108, v121
	v_sub_f32_e32 v109, v109, v121
	v_sub_f32_e32 v110, v110, v121
	v_sub_f32_e32 v111, v111, v121
	v_sub_f32_e32 v112, v112, v121
	v_sub_f32_e32 v113, v113, v121
	v_sub_f32_e32 v114, v114, v121
	v_sub_f32_e32 v115, v115, v121
	v_sub_f32_e32 v116, v116, v121
	v_sub_f32_e32 v117, v117, v121
	v_sub_f32_e32 v118, v118, v121
	v_sub_f32_e32 v119, v119, v121
	v_sub_f32_e32 v140, v140, v121
	v_sub_f32_e32 v141, v141, v121
	v_sub_f32_e32 v142, v142, v121
	v_sub_f32_e32 v143, v143, v121
	v_mul_f32_e32 v32, v32, v164
	v_mul_f32_e32 v33, v33, v164
	v_mul_f32_e32 v34, v34, v164
	v_mul_f32_e32 v35, v35, v164
	v_mul_f32_e32 v36, v36, v164
	v_mul_f32_e32 v37, v37, v164
	v_mul_f32_e32 v38, v38, v164
	v_mul_f32_e32 v39, v39, v164
	v_mul_f32_e32 v40, v40, v164
	v_mul_f32_e32 v41, v41, v164
	v_mul_f32_e32 v42, v42, v164
	v_mul_f32_e32 v43, v43, v164
	v_mul_f32_e32 v44, v44, v164
	v_mul_f32_e32 v45, v45, v164
	v_mul_f32_e32 v46, v46, v164
	v_mul_f32_e32 v47, v47, v164
	v_mul_f32_e32 v132, v132, v164
	v_mul_f32_e32 v133, v133, v164
	v_mul_f32_e32 v134, v134, v164
	v_mul_f32_e32 v135, v135, v164
	s_branch .Lback_a

.LBB0_152:
	v_lshl_add_u32 v137, v102, 6, v78
	ds_read_b128 v[198:201], v137 offset:39936
	ds_read_b128 v[202:205], v137 offset:48384
	ds_read_b128 v[206:209], v137 offset:56832
	ds_read_b128 v[232:235], v137 offset:65280
	s_waitcnt lgkmcnt(4)
	v_mfma_f32_16x16x32_bf16 v[104:107], v[166:169], v[8:11], v[140:143]
	v_add_f32_e32 v112, v112, v140
	v_add_f32_e32 v113, v113, v140
	v_mfma_f32_16x16x32_bf16 v[108:111], v[174:177], v[8:11], v[140:143]
	v_add_f32_e32 v114, v114, v140
	v_add_f32_e32 v115, v115, v140
	v_mfma_f32_16x16x32_bf16 v[104:107], v[170:173], v[12:15], v[104:107]
	v_add_f32_e32 v116, v116, v140
	v_add_f32_e32 v117, v117, v140
	v_mfma_f32_16x16x32_bf16 v[108:111], v[178:181], v[12:15], v[108:111]
	v_add_f32_e32 v118, v118, v140
	v_add_f32_e32 v119, v119, v140
	ds_read_b128 v[236:239], v211 offset:0
	ds_read_b128 v[240:243], v211 offset:2304
	ds_read_b128 v[244:247], v211 offset:4608
	ds_read_b128 v[228:231], v211 offset:6912
	v_mfma_f32_16x16x32_bf16 v[112:115], v[182:185], v[8:11], v[112:115]
	v_mfma_f32_16x16x32_bf16 v[116:119], v[190:193], v[8:11], v[116:119]
	v_mfma_f32_16x16x32_bf16 v[112:115], v[186:189], v[12:15], v[112:115]
	v_mfma_f32_16x16x32_bf16 v[116:119], v[194:197], v[12:15], v[116:119]
	v_max3_f32 v121, v104, v105, v106
	v_max3_f32 v122, v108, v109, v110
	v_max3_f32 v121, v121, v107, v111
	s_nop 3
	v_max3_f32 v123, v112, v113, v114
	v_max3_f32 v122, v122, v116, v117
	v_max3_f32 v121, v121, v115, v118
	v_max3_f32 v121, v121, v122, v123
	v_max_f32_e32 v121, v121, v119
	v_cmp_lt_f32_e32 vcc, 0x41000000, v121
	s_cbranch_vccnz .Lrare_a
.Lback_a:
	v_exp_f32_e32 v104, v104
	v_exp_f32_e32 v105, v105
	v_exp_f32_e32 v106, v106
	v_exp_f32_e32 v107, v107
	v_exp_f32_e32 v108, v108
	v_exp_f32_e32 v109, v109
	v_exp_f32_e32 v110, v110
	v_exp_f32_e32 v111, v111
	v_exp_f32_e32 v112, v112
	v_exp_f32_e32 v113, v113
	v_exp_f32_e32 v114, v114
	v_exp_f32_e32 v115, v115
	v_exp_f32_e32 v116, v116
	v_exp_f32_e32 v117, v117
	v_exp_f32_e32 v118, v118
	v_exp_f32_e32 v119, v119
	v_cvt_pk_bf16_f32 v124, v104, v105
	v_cvt_pk_bf16_f32 v125, v106, v107
	v_cvt_pk_bf16_f32 v126, v108, v109
	v_cvt_pk_bf16_f32 v127, v110, v111
	v_cvt_pk_bf16_f32 v128, v112, v113
	v_cvt_pk_bf16_f32 v129, v114, v115
	v_cvt_pk_bf16_f32 v130, v116, v117
	v_cvt_pk_bf16_f32 v131, v118, v119
	s_waitcnt lgkmcnt(4)
	v_mfma_f32_16x16x32_bf16 v[32:35], v[198:201], v[124:127], v[32:35]
	v_mfma_f32_16x16x32_bf16 v[36:39], v[202:205], v[124:127], v[36:39]
	v_mfma_f32_16x16x32_bf16 v[40:43], v[206:209], v[124:127], v[40:43]
	v_mfma_f32_16x16x32_bf16 v[44:47], v[232:235], v[124:127], v[44:47]
	v_mfma_f32_16x16x32_bf16 v[132:135], v[144:147], v[124:127], v[132:135]
	s_waitcnt lgkmcnt(0)
	v_mfma_f32_16x16x32_bf16 v[32:35], v[236:239], v[128:131], v[32:35]
	v_mfma_f32_16x16x32_bf16 v[36:39], v[240:243], v[128:131], v[36:39]
	v_mfma_f32_16x16x32_bf16 v[132:135], v[144:147], v[128:131], v[132:135]
	v_mfma_f32_16x16x32_bf16 v[40:43], v[244:247], v[128:131], v[40:43]
	v_mfma_f32_16x16x32_bf16 v[44:47], v[228:231], v[128:131], v[44:47]
	s_add_i32 s16, s5, -1
	s_cmp_lg_u32 s14, s16
	s_cbranch_scc1 .LBB0_131
.LBB0_153:
	s_nop 7
	v_mov_b32_e32 v102, v132
	v_div_scale_f32 v103, s[18:19], v102, v102, 1.0
	v_rcp_f32_e32 v104, v103
	s_nop 0
	v_fma_f32 v105, -v103, v104, 1.0
	v_fmac_f32_e32 v104, v105, v104
	v_div_scale_f32 v105, vcc, 1.0, v102, 1.0
	v_mul_f32_e32 v106, v105, v104
	v_fma_f32 v107, -v103, v106, v105
	v_fmac_f32_e32 v106, v107, v104
	v_fma_f32 v103, -v103, v106, v105
	v_div_fmas_f32 v103, v103, v104, v106
	v_add_u32_e32 v104, s2, v63
	v_div_fixup_f32 v102, v103, v102, 1.0
	v_ashrrev_i32_e32 v105, 31, v104
	v_lshlrev_b64 v[104:105], 11, v[104:105]
	v_pk_mul_f32 v[108:109], v[32:33], v[102:103] op_sel_hi:[1,0]
	v_lshl_add_u64 v[104:105], v[76:77], 0, v[104:105]
	v_pk_mul_f32 v[106:107], v[34:35], v[102:103] op_sel_hi:[1,0]
	v_cvt_pk_bf16_f32 v108, v108, v109
	s_nop 0
	v_cvt_pk_bf16_f32 v109, v106, v107
	global_store_dwordx2 v[104:105], v[108:109], off
	v_pk_mul_f32 v[108:109], v[36:37], v[102:103] op_sel_hi:[1,0]
	v_pk_mul_f32 v[106:107], v[38:39], v[102:103] op_sel_hi:[1,0]
	v_cvt_pk_bf16_f32 v108, v108, v109
	s_nop 0
	v_cvt_pk_bf16_f32 v109, v106, v107
	global_store_dwordx2 v[104:105], v[108:109], off offset:32
	v_pk_mul_f32 v[106:107], v[42:43], v[102:103] op_sel_hi:[1,0]
	v_pk_mul_f32 v[108:109], v[40:41], v[102:103] op_sel_hi:[1,0]
	s_nop 0
	v_cvt_pk_bf16_f32 v108, v108, v109
	v_cvt_pk_bf16_f32 v109, v106, v107
	v_pk_mul_f32 v[106:107], v[46:47], v[102:103] op_sel_hi:[1,0]
	v_pk_mul_f32 v[102:103], v[44:45], v[102:103] op_sel_hi:[1,0]
	global_store_dwordx2 v[104:105], v[108:109], off offset:64
	v_cvt_pk_bf16_f32 v102, v102, v103
	v_cvt_pk_bf16_f32 v103, v106, v107
	global_store_dwordx2 v[104:105], v[102:103], off offset:96
	s_add_i32 s14, s14, 1
	s_cmp_lt_i32 s14, s5
	s_cbranch_scc0 .LBB0_132
	s_branch .LBB0_133
.LBB0_154:
	v_lshl_add_u32 v137, v102, 6, v78
	ds_read_b128 v[198:201], v137 offset:39936
	ds_read_b128 v[202:205], v137 offset:48384
	ds_read_b128 v[206:209], v137 offset:56832
	ds_read_b128 v[232:235], v137 offset:65280
	s_waitcnt lgkmcnt(4)
	v_mfma_f32_16x16x32_bf16 v[104:107], v[166:169], v[8:11], v[140:143]
	v_add_f32_e32 v112, v112, v140
	v_add_f32_e32 v113, v113, v140
	v_mfma_f32_16x16x32_bf16 v[108:111], v[174:177], v[8:11], v[140:143]
	v_add_f32_e32 v114, v114, v140
	v_add_f32_e32 v115, v115, v140
	v_mfma_f32_16x16x32_bf16 v[104:107], v[170:173], v[12:15], v[104:107]
	v_add_f32_e32 v116, v116, v140
	v_add_f32_e32 v117, v117, v140
	v_mfma_f32_16x16x32_bf16 v[108:111], v[178:181], v[12:15], v[108:111]
	v_add_f32_e32 v118, v118, v140
	v_add_f32_e32 v119, v119, v140
	ds_read_b128 v[236:239], v211 offset:18432
	ds_read_b128 v[240:243], v211 offset:20736
	ds_read_b128 v[244:247], v211 offset:23040
	ds_read_b128 v[228:231], v211 offset:25344
	v_mfma_f32_16x16x32_bf16 v[112:115], v[182:185], v[8:11], v[112:115]
	v_mfma_f32_16x16x32_bf16 v[116:119], v[190:193], v[8:11], v[116:119]
	v_mfma_f32_16x16x32_bf16 v[112:115], v[186:189], v[12:15], v[112:115]
	v_mfma_f32_16x16x32_bf16 v[116:119], v[194:197], v[12:15], v[116:119]
	v_max3_f32 v121, v104, v105, v106
	v_max3_f32 v122, v108, v109, v110
	v_max3_f32 v121, v121, v107, v111
	s_nop 3
	v_max3_f32 v123, v112, v113, v114
	v_max3_f32 v122, v122, v116, v117
	v_max3_f32 v121, v121, v115, v118
	v_max3_f32 v121, v121, v122, v123
	v_max_f32_e32 v121, v121, v119
	v_cmp_lt_f32_e32 vcc, 0x41000000, v121
	s_cbranch_vccnz .Lrare_b
.Lback_b:
	v_exp_f32_e32 v104, v104
	v_exp_f32_e32 v105, v105
	v_exp_f32_e32 v106, v106
	v_exp_f32_e32 v107, v107
	v_exp_f32_e32 v108, v108
	v_exp_f32_e32 v109, v109
	v_exp_f32_e32 v110, v110
	v_exp_f32_e32 v111, v111
	v_exp_f32_e32 v112, v112
	v_exp_f32_e32 v113, v113
	v_exp_f32_e32 v114, v114
	v_exp_f32_e32 v115, v115
	v_exp_f32_e32 v116, v116
	v_exp_f32_e32 v117, v117
	v_exp_f32_e32 v118, v118
	v_exp_f32_e32 v119, v119
	v_cvt_pk_bf16_f32 v124, v104, v105
	v_cvt_pk_bf16_f32 v125, v106, v107
	v_cvt_pk_bf16_f32 v126, v108, v109
	v_cvt_pk_bf16_f32 v127, v110, v111
	v_cvt_pk_bf16_f32 v128, v112, v113
	v_cvt_pk_bf16_f32 v129, v114, v115
	v_cvt_pk_bf16_f32 v130, v116, v117
	v_cvt_pk_bf16_f32 v131, v118, v119
	s_waitcnt lgkmcnt(4)
	v_mfma_f32_16x16x32_bf16 v[32:35], v[198:201], v[124:127], v[32:35]
	v_mfma_f32_16x16x32_bf16 v[36:39], v[202:205], v[124:127], v[36:39]
	v_mfma_f32_16x16x32_bf16 v[40:43], v[206:209], v[124:127], v[40:43]
	v_mfma_f32_16x16x32_bf16 v[44:47], v[232:235], v[124:127], v[44:47]
	v_mfma_f32_16x16x32_bf16 v[132:135], v[144:147], v[124:127], v[132:135]
	s_waitcnt lgkmcnt(0)
	v_mfma_f32_16x16x32_bf16 v[32:35], v[236:239], v[128:131], v[32:35]
	v_mfma_f32_16x16x32_bf16 v[36:39], v[240:243], v[128:131], v[36:39]
	v_mfma_f32_16x16x32_bf16 v[132:135], v[144:147], v[128:131], v[132:135]
	v_mfma_f32_16x16x32_bf16 v[40:43], v[244:247], v[128:131], v[40:43]
	v_mfma_f32_16x16x32_bf16 v[44:47], v[228:231], v[128:131], v[44:47]
	s_add_i32 s15, s5, -1
	s_cmp_lg_u32 s14, s15
	s_cbranch_scc1 .LBB0_141

.LBB0_156:
	v_lshl_add_u32 v137, v102, 6, v78
	ds_read_b128 v[198:201], v137 offset:39936
	ds_read_b128 v[202:205], v137 offset:48384
	ds_read_b128 v[206:209], v137 offset:56832
	ds_read_b128 v[232:235], v137 offset:65280
	s_waitcnt lgkmcnt(4)
	v_mfma_f32_16x16x32_bf16 v[104:107], v[166:169], v[8:11], v[140:143]
	v_add_f32_e32 v112, v112, v140
	v_add_f32_e32 v113, v113, v140
	v_mfma_f32_16x16x32_bf16 v[108:111], v[174:177], v[8:11], v[140:143]
	v_add_f32_e32 v114, v114, v140
	v_add_f32_e32 v115, v115, v140
	v_mfma_f32_16x16x32_bf16 v[104:107], v[170:173], v[12:15], v[104:107]
	v_add_f32_e32 v116, v116, v140
	v_add_f32_e32 v117, v117, v140
	v_mfma_f32_16x16x32_bf16 v[108:111], v[178:181], v[12:15], v[108:111]
	v_add_f32_e32 v118, v118, v140
	v_add_f32_e32 v119, v119, v140
	ds_read_b128 v[236:239], v211 offset:36864
	ds_read_b128 v[240:243], v211 offset:39168
	ds_read_b128 v[244:247], v211 offset:41472
	ds_read_b128 v[228:231], v211 offset:43776
	v_mfma_f32_16x16x32_bf16 v[112:115], v[182:185], v[8:11], v[112:115]
	v_mfma_f32_16x16x32_bf16 v[116:119], v[190:193], v[8:11], v[116:119]
	v_mfma_f32_16x16x32_bf16 v[112:115], v[186:189], v[12:15], v[112:115]
	v_mfma_f32_16x16x32_bf16 v[116:119], v[194:197], v[12:15], v[116:119]
	v_max3_f32 v121, v104, v105, v106
	v_max3_f32 v122, v108, v109, v110
	v_max3_f32 v121, v121, v107, v111
	s_nop 3
	v_max3_f32 v123, v112, v113, v114
	v_max3_f32 v122, v122, v116, v117
	v_max3_f32 v121, v121, v115, v118
	v_max3_f32 v121, v121, v122, v123
	v_max_f32_e32 v121, v121, v119
	v_cmp_lt_f32_e32 vcc, 0x41000000, v121
	s_cbranch_vccnz .Lrare_c
.Lback_c:
	v_exp_f32_e32 v104, v104
	v_exp_f32_e32 v105, v105
	v_exp_f32_e32 v106, v106
	v_exp_f32_e32 v107, v107
	v_exp_f32_e32 v108, v108
	v_exp_f32_e32 v109, v109
	v_exp_f32_e32 v110, v110
	v_exp_f32_e32 v111, v111
	v_exp_f32_e32 v112, v112
	v_exp_f32_e32 v113, v113
	v_exp_f32_e32 v114, v114
	v_exp_f32_e32 v115, v115
	v_exp_f32_e32 v116, v116
	v_exp_f32_e32 v117, v117
	v_exp_f32_e32 v118, v118
	v_exp_f32_e32 v119, v119
	v_cvt_pk_bf16_f32 v124, v104, v105
	v_cvt_pk_bf16_f32 v125, v106, v107
	v_cvt_pk_bf16_f32 v126, v108, v109
	v_cvt_pk_bf16_f32 v127, v110, v111
	v_cvt_pk_bf16_f32 v128, v112, v113
	v_cvt_pk_bf16_f32 v129, v114, v115
	v_cvt_pk_bf16_f32 v130, v116, v117
	v_cvt_pk_bf16_f32 v131, v118, v119
	s_waitcnt lgkmcnt(4)
	v_mfma_f32_16x16x32_bf16 v[32:35], v[198:201], v[124:127], v[32:35]
	v_mfma_f32_16x16x32_bf16 v[36:39], v[202:205], v[124:127], v[36:39]
	v_mfma_f32_16x16x32_bf16 v[40:43], v[206:209], v[124:127], v[40:43]
	v_mfma_f32_16x16x32_bf16 v[44:47], v[232:235], v[124:127], v[44:47]
	v_mfma_f32_16x16x32_bf16 v[132:135], v[144:147], v[124:127], v[132:135]
	s_waitcnt lgkmcnt(0)
	v_mfma_f32_16x16x32_bf16 v[32:35], v[236:239], v[128:131], v[32:35]
	v_mfma_f32_16x16x32_bf16 v[36:39], v[240:243], v[128:131], v[36:39]
	v_mfma_f32_16x16x32_bf16 v[132:135], v[144:147], v[128:131], v[132:135]
	v_mfma_f32_16x16x32_bf16 v[40:43], v[244:247], v[128:131], v[40:43]
	v_mfma_f32_16x16x32_bf16 v[44:47], v[228:231], v[128:131], v[44:47]
	s_add_i32 s17, s5, -1
	s_cmp_lg_u32 s14, s17
	s_cbranch_scc1 .LBB0_151
.LBB0_157:
	s_nop 7
	v_mov_b32_e32 v102, v132
	v_div_scale_f32 v103, s[18:19], v102, v102, 1.0
	v_rcp_f32_e32 v104, v103
	s_nop 0
	v_fma_f32 v105, -v103, v104, 1.0
	v_fmac_f32_e32 v104, v105, v104
	v_div_scale_f32 v105, vcc, 1.0, v102, 1.0
	v_mul_f32_e32 v106, v105, v104
	v_fma_f32 v107, -v103, v106, v105
	v_fmac_f32_e32 v106, v107, v104
	v_fma_f32 v103, -v103, v106, v105
	v_div_fmas_f32 v103, v103, v104, v106
	v_add_u32_e32 v104, s2, v63
	v_div_fixup_f32 v102, v103, v102, 1.0
	v_ashrrev_i32_e32 v105, 31, v104
	v_lshlrev_b64 v[104:105], 11, v[104:105]
	v_pk_mul_f32 v[108:109], v[32:33], v[102:103] op_sel_hi:[1,0]
	v_lshl_add_u64 v[104:105], v[76:77], 0, v[104:105]
	v_pk_mul_f32 v[106:107], v[34:35], v[102:103] op_sel_hi:[1,0]
	v_cvt_pk_bf16_f32 v108, v108, v109
	s_nop 0
	v_cvt_pk_bf16_f32 v109, v106, v107
	global_store_dwordx2 v[104:105], v[108:109], off
	v_pk_mul_f32 v[108:109], v[36:37], v[102:103] op_sel_hi:[1,0]
	v_pk_mul_f32 v[106:107], v[38:39], v[102:103] op_sel_hi:[1,0]
	v_cvt_pk_bf16_f32 v108, v108, v109
	s_nop 0
	v_cvt_pk_bf16_f32 v109, v106, v107
	global_store_dwordx2 v[104:105], v[108:109], off offset:32
	v_pk_mul_f32 v[106:107], v[42:43], v[102:103] op_sel_hi:[1,0]
	v_pk_mul_f32 v[108:109], v[40:41], v[102:103] op_sel_hi:[1,0]
	s_nop 0
	v_cvt_pk_bf16_f32 v108, v108, v109
	v_cvt_pk_bf16_f32 v109, v106, v107
	v_pk_mul_f32 v[106:107], v[46:47], v[102:103] op_sel_hi:[1,0]
	v_pk_mul_f32 v[102:103], v[44:45], v[102:103] op_sel_hi:[1,0]
	global_store_dwordx2 v[104:105], v[108:109], off offset:64
	v_cvt_pk_bf16_f32 v102, v102, v103
	v_cvt_pk_bf16_f32 v103, v106, v107
	global_store_dwordx2 v[104:105], v[102:103], off offset:96
	s_add_i32 s14, s14, 1
	s_cmp_lt_i32 s14, s5
	s_cbranch_scc1 .LBB0_122

.LBB0_159:
	v_mov_b32_e32 v100, 0
	s_waitcnt vmcnt(2)
	v_mov_b64_e32 v[14:15], v[6:7]
	v_mov_b32_e32 v101, 0xf149f2ca
	v_mov_b32_e32 v132, 0
	v_mov_b32_e32 v133, 0
	v_mov_b32_e32 v134, 0
	v_mov_b32_e32 v135, 0
	v_mov_b32_e32 v140, 0x42c80000
	v_mov_b32_e32 v141, 0x42c80000
	v_mov_b32_e32 v142, 0x42c80000
	v_mov_b32_e32 v143, 0x42c80000
	v_mov_b64_e32 v[12:13], v[4:5]
	v_mov_b64_e32 v[10:11], v[2:3]
	v_mov_b64_e32 v[8:9], v[0:1]
	v_mov_b32_e32 v32, 0
	v_mov_b32_e32 v33, v100
	v_mov_b32_e32 v34, v100
	v_mov_b32_e32 v35, v100
	v_mov_b32_e32 v36, v100
	v_mov_b32_e32 v37, v100
	v_mov_b32_e32 v38, v100
	v_mov_b32_e32 v39, v100
	v_mov_b32_e32 v40, v100
	v_mov_b32_e32 v41, v100
	v_mov_b32_e32 v42, v100
	v_mov_b32_e32 v43, v100
	v_mov_b32_e32 v44, v100
	v_mov_b32_e32 v45, v100
	v_mov_b32_e32 v46, v100
	v_mov_b32_e32 v47, v100
	s_add_i32 s16, s5, -2
	s_cmp_lg_u32 s14, s16
	s_cbranch_scc0 .LBB0_128
	s_branch .LBB0_129
.LBB0_160:
	v_mov_b32_e32 v100, 0
	s_waitcnt vmcnt(2)
	v_mov_b64_e32 v[14:15], v[6:7]
	v_mov_b32_e32 v101, 0xf149f2ca
	v_mov_b32_e32 v132, 0
	v_mov_b32_e32 v133, 0
	v_mov_b32_e32 v134, 0
	v_mov_b32_e32 v135, 0
	v_mov_b32_e32 v140, 0x42c80000
	v_mov_b32_e32 v141, 0x42c80000
	v_mov_b32_e32 v142, 0x42c80000
	v_mov_b32_e32 v143, 0x42c80000
	v_mov_b64_e32 v[12:13], v[4:5]
	v_mov_b64_e32 v[10:11], v[2:3]
	v_mov_b64_e32 v[8:9], v[0:1]
	v_mov_b32_e32 v32, 0
	v_mov_b32_e32 v33, v100
	v_mov_b32_e32 v34, v100
	v_mov_b32_e32 v35, v100
	v_mov_b32_e32 v36, v100
	v_mov_b32_e32 v37, v100
	v_mov_b32_e32 v38, v100
	v_mov_b32_e32 v39, v100
	v_mov_b32_e32 v40, v100
	v_mov_b32_e32 v41, v100
	v_mov_b32_e32 v42, v100
	v_mov_b32_e32 v43, v100
	v_mov_b32_e32 v44, v100
	v_mov_b32_e32 v45, v100
	v_mov_b32_e32 v46, v100
	v_mov_b32_e32 v47, v100
	s_add_i32 s15, s5, -2
	s_cmp_lg_u32 s14, s15
	s_cbranch_scc0 .LBB0_138
	s_branch .LBB0_139
.LBB0_161:
	v_mov_b32_e32 v100, 0
	s_waitcnt vmcnt(2)
	v_mov_b64_e32 v[14:15], v[6:7]
	v_mov_b32_e32 v101, 0xf149f2ca
	v_mov_b32_e32 v132, 0
	v_mov_b32_e32 v133, 0
	v_mov_b32_e32 v134, 0
	v_mov_b32_e32 v135, 0
	v_mov_b32_e32 v140, 0x42c80000
	v_mov_b32_e32 v141, 0x42c80000
	v_mov_b32_e32 v142, 0x42c80000
	v_mov_b32_e32 v143, 0x42c80000
	v_mov_b64_e32 v[12:13], v[4:5]
	v_mov_b64_e32 v[10:11], v[2:3]
	v_mov_b64_e32 v[8:9], v[0:1]
	v_mov_b32_e32 v32, 0
	v_mov_b32_e32 v33, v100
	v_mov_b32_e32 v34, v100
	v_mov_b32_e32 v35, v100
	v_mov_b32_e32 v36, v100
	v_mov_b32_e32 v37, v100
	v_mov_b32_e32 v38, v100
	v_mov_b32_e32 v39, v100
	v_mov_b32_e32 v40, v100
	v_mov_b32_e32 v41, v100
	v_mov_b32_e32 v42, v100
	v_mov_b32_e32 v43, v100
	v_mov_b32_e32 v44, v100
	v_mov_b32_e32 v45, v100
	v_mov_b32_e32 v46, v100
	v_mov_b32_e32 v47, v100
	s_add_i32 s17, s5, -2
	s_cmp_lg_u32 s14, s17
	s_cbranch_scc0 .LBB0_148
	s_branch .LBB0_149
